# attention block loop: one static s_setprio 1 for waves 4-7 before the loop, reset to 0 after it
# baseline (speedup 1.0000x reference)
.LBB0_826:
	s_mov_b32 m0, s3
	s_add_i32 s2, s2, -1
	global_load_lds_dwordx4 v[10:11], off
	s_addk_i32 s3, 0x400
	s_cmp_lg_u32 s2, 0
	v_lshl_add_u64 v[10:11], v[10:11], 0, 32
	s_cbranch_scc1 .LBB0_826
	s_add_u32 s51, s6, 0x34000000
	s_addc_u32 s70, s7, 0
	s_add_u32 s71, s6, 0x1800000
	s_addc_u32 s72, s7, 0
	s_lshl_b64 s[2:3], s[16:17], 8
	s_add_u32 s48, s71, s2
	s_addc_u32 s49, s72, s3
	s_add_u32 s2, s51, s4
	s_addc_u32 s3, s70, s5
	s_add_u32 s64, s2, s1
	s_movk_i32 s1, 0x70
	v_lshlrev_b32_e32 v10, 8, v15
	v_bitop3_b32 v16, v16, v0, s1 bitop3:0x78
	v_add3_u32 v16, 0, v16, v10
	s_waitcnt vmcnt(0)
	s_waitcnt vmcnt(0)
	ds_write_b128 v16, v[2:5] offset:32768
	ds_write_b128 v16, v[6:9] offset:40960
	v_lshlrev_b32_e32 v5, 1, v15
	v_lshrrev_b32_e32 v7, 5, v0
	v_and_b32_e32 v5, 8, v5
	v_and_b32_e32 v206, 4, v7
	v_and_or_b32 v6, v15, 16, v5
	v_and_or_b32 v8, v15, 3, v206
	v_or_b32_e32 v15, 32, v15
	v_lshlrev_b32_e32 v3, 3, v0
	v_and_or_b32 v5, v15, 48, v5
	v_and_b32_e32 v4, 0x78, v3
	v_lshrrev_b32_e32 v6, 1, v6
	v_bfe_u32 v7, v3, 5, 2
	v_lshrrev_b32_e32 v5, 1, v5
	v_or_b32_e32 v6, v6, v7
	v_lshlrev_b32_e32 v4, 1, v4
	v_or_b32_e32 v5, v5, v7
	v_lshlrev_b32_e32 v6, 9, v6
	v_lshlrev_b32_e32 v8, 6, v8
	v_and_b32_e32 v9, 48, v4
	v_lshlrev_b32_e32 v5, 9, v5
	v_or3_b32 v6, v6, v8, v9
	v_or3_b32 v5, v5, v8, v9
	v_lshlrev_b32_e32 v9, 1, v0
	v_lshrrev_b32_e32 v2, 5, v210
	v_and_b32_e32 v8, 0xc0, v1
	v_and_b32_e32 v9, 32, v9
	v_and_b32_e32 v3, 0x118, v3
	s_addc_u32 s65, s3, 0
	v_and_b32_e32 v11, 0x70, v0
	v_or3_b32 v3, v9, v8, v3
	v_lshlrev_b32_e32 v207, 4, v205
	v_lshlrev_b32_e32 v8, 4, v2
	v_bitop3_b32 v7, v4, v10, v11 bitop3:0xde
	v_and_b32_e32 v9, 0x70, v207
	v_or_b32_e32 v11, 32, v8
	v_or_b32_e32 v15, 64, v8
	v_or_b32_e32 v16, 0x60, v8
	s_cmp_lg_u32 0, -1
	v_mov_b32_e32 v197, 0
	v_bitop3_b32 v10, v8, v14, v9 bitop3:0xde
	v_bitop3_b32 v11, v11, v14, v9 bitop3:0xde
	v_bitop3_b32 v15, v15, v14, v9 bitop3:0xde
	v_bitop3_b32 v9, v16, v14, v9 bitop3:0xde
	s_cselect_b32 s1, 0, 0
	s_mov_b32 s17, 0
	v_or_b32_e32 v194, v4, v13
	v_mov_b32_e32 v195, v197
	v_lshlrev_b32_e32 v208, 2, v2
	v_cmp_gt_u32_e64 s[4:5], 32, v210
	v_or_b32_e32 v209, v8, v14
	v_add_u32_e32 v212, s1, v3
	v_or_b32_e32 v213, v12, v8
	v_add_u32_e32 v198, v13, v4
	v_mov_b32_e32 v199, v197
	s_mov_b32 s73, 0x40000
	s_mov_b32 s74, 0x60000
	s_mov_b32 s75, 0xff800000
	s_mov_b32 s76, 0x41000000
	s_mov_b32 s50, 0x3e0293ee
	s_mov_b32 s77, 0x80000
	s_mov_b32 s78, 0xa0000
	s_mov_b32 s79, 0x20000
	s_mov_b64 s[52:53], 0x800
	s_mov_b64 s[54:55], 0x2800
	v_add_u32_e32 v214, 0, v6
	v_add_u32_e32 v215, 0, v5
	v_add_u32_e32 v216, 0, v10
	v_add_u32_e32 v217, 0, v11
	v_add_u32_e32 v218, 0, v15
	v_add_u32_e32 v219, 0, v9
	v_mov_b32_e32 v220, 0xf149f2ca
	v_add_u32_e32 v221, 0, v7
	s_mov_b32 s80, 0
	s_mov_b32 s81, s96
	s_mov_b32 s82, s0
	s_mov_b64 s[56:57], s[64:65]
	s_mov_b64 s[60:61], s[68:69]
	s_mov_b64 s[58:59], s[66:67]
	v_readlane_b32 s99, v255, 12
	s_cmp_ge_u32 s99, 4
	s_cbranch_scc0 .Lmy_att_prio
	s_setprio 1
.Lmy_att_prio:
	s_waitcnt lgkmcnt(0)
	s_barrier
	s_branch .LBB0_829

.LBB0_863:
	s_setprio 0
	s_waitcnt vmcnt(0)
	v_readlane_b32 s40, v255, 15
	v_readlane_b32 s44, v255, 17
	s_barrier
	v_readlane_b32 s41, v255, 16
	v_readlane_b32 s45, v255, 18
	s_branch .LBB0_865
